# batched residual epilogue for outproj/down tiles: loads issued 2x16 ahead, fmac, stores (was load-wait-fmac-store per element)
# speedup vs baseline: 1.1988x; 1.0623x over previous
; DI int tile_of(int i, int ntiles) {
;   const int G = gridDim.x, b = blockIdx.x;
;   if (G & 7) { int L = b + i * G; return L < ntiles ? L : -1; }
;   const int q = (ntiles + 7) >> 3, nb = G >> 3, x = b & 7, loc = (b >> 3) + i * nb;
;   if (loc >= q) return -1;
;   const int L = x * q + loc;
;   return L < ntiles ? L : -1;
; }
; DI void outproj256(const Params& p, int layer, char* smem) {
;   const bf16_t* Yb = (const bf16_t*)(p.ws + O_Y);
;   const bf16_t* W = (const bf16_t*)(p.ws + O_WOUT) + (size_t)layer * DM * DM;
;   const float* g1 = (const float*)(p.ws + O_MODS) + (size_t)(layer * 2) * 12288 + 2 * DM;
;   float* X = (float*)(p.ws + O_X);
;   for (int i = 0;; ++i) {
;     const int L = tile_of(i, 32 * 8);
;     if (L < 0) break;
;     int tm, tn; tile_mn(L, 32, 8, tm, tn);
.LBB0_913:
	s_or_b64 exec, exec, s[0:1]
	v_readlane_b32 s0, v254, 47
	v_readlane_b32 s1, v254, 48
	s_mov_b32 s4, s0
	s_lshl_b32 s0, s0, 23
	v_readlane_b32 s1, v252, 43
	s_add_u32 s10, s1, s0
	v_readlane_b32 s0, v252, 44
	s_mul_i32 s22, s4, 0x6000
	s_addc_u32 s11, s0, 0
	s_lshl_b64 s[0:1], s[22:23], 2
	s_add_u32 s89, s36, s0
	s_addc_u32 s42, s37, s1
	s_add_u32 s0, s89, 0xc404000
	s_addc_u32 s1, s42, 0
	s_mov_b32 s12, 0
	s_waitcnt lgkmcnt(0)
	s_barrier
	s_branch .LBB0_915
.LBB0_915:
	s_and_b64 vcc, exec, s[40:41]
	s_mov_b64 s[4:5], -1
	s_cbranch_vccnz .LBB0_921
	s_mul_i32 s4, s12, s49
	s_add_i32 s4, s4, s2
	s_cmpk_lt_i32 s4, 0x100
	s_cselect_b32 s6, s4, -1
	s_cbranch_execz .LBB0_922

; DI int tid512() { int t = threadIdx.x; asm volatile("" : "+v"(t)); return t; }
; DI void outproj256(const Params& p, int layer, char* smem) {
;     ...
;     const int t = tid512(), lane = t & 63, w = t >> 6, wm = w >> 2, wn = w & 3, r = lane & 31, h = lane >> 5;
; #pragma unroll
;     for (int mi = 0; mi < 4; ++mi)
; #pragma unroll
;       for (int ni = 0; ni < 2; ++ni) {
;         const int col = tn * 256 + 64 * wn + 32 * ni + r;
;         const float gg = g1[col];
; #pragma unroll
;         for (int reg = 0; reg < 16; ++reg) {
;           const int row = 256 + tm * 256 + 128 * wm + 32 * mi + (reg & 3) + 8 * (reg >> 2) + 4 * h;
;           const float res = (layer == 0) ? __builtin_nontemporal_load(p.x + (size_t)(row - 256) * DM + col) : X[(size_t)row * DM + col];
;           X[(size_t)row * DM + col] = res + gg * acc[mi][ni][reg];
;         }
;       }
.LBB0_925:
	s_waitcnt vmcnt(0)
	v_and_b32_e32 v130, 0xdf, v0
	v_or_b32_e32 v130, s4, v130
	v_lshlrev_b32_e32 v130, 2, v130
	global_load_dword v137, v130, s[0:1]
	global_load_dword v138, v130, s[0:1] offset:128
	v_ashrrev_i32_e32 v131, 1, v0
	v_and_b32_e32 v131, 0xffffff80, v131
	v_add_u32_e32 v131, s22, v131
	v_lshrrev_b32_e32 v132, 3, v0
	v_and_or_b32 v131, v132, 4, v131
	v_lshl_add_u32 v133, v131, 13, v130
	v_add_u32_e32 v134, 0x2000, v133
	v_add_u32_e32 v135, 0x4000, v133
	v_add_u32_e32 v136, 0x6000, v133
	s_add_u32 s56, s68, 0xffe00000
	s_addc_u32 s57, s69, -1
	s_cmp_lg_u64 s[34:35], 0
	s_cselect_b32 s52, s90, s56
	s_cselect_b32 s53, s91, s57
	s_mov_b64 s[54:55], s[90:91]
	s_add_i32 s12, s12, 1
	s_add_u32 s56, s52, 0x0
	s_addc_u32 s57, s53, 0
	global_load_dword v193, v133, s[56:57]
	global_load_dword v194, v133, s[56:57] offset:128
	global_load_dword v195, v134, s[56:57]
	global_load_dword v196, v134, s[56:57] offset:128
	global_load_dword v197, v135, s[56:57]
	global_load_dword v198, v135, s[56:57] offset:128
	global_load_dword v199, v136, s[56:57]
	global_load_dword v200, v136, s[56:57] offset:128
	s_add_u32 s56, s52, 0x10000
	s_addc_u32 s57, s53, 0
	global_load_dword v201, v133, s[56:57]
	global_load_dword v202, v133, s[56:57] offset:128
	global_load_dword v203, v134, s[56:57]
	global_load_dword v204, v134, s[56:57] offset:128
	global_load_dword v205, v135, s[56:57]
	global_load_dword v206, v135, s[56:57] offset:128
	global_load_dword v207, v136, s[56:57]
	global_load_dword v208, v136, s[56:57] offset:128
	s_add_u32 s56, s52, 0x20000
	s_addc_u32 s57, s53, 0
	global_load_dword v209, v133, s[56:57]
	global_load_dword v210, v133, s[56:57] offset:128
	global_load_dword v211, v134, s[56:57]
	global_load_dword v212, v134, s[56:57] offset:128
	global_load_dword v213, v135, s[56:57]
	global_load_dword v214, v135, s[56:57] offset:128
	global_load_dword v215, v136, s[56:57]
	global_load_dword v216, v136, s[56:57] offset:128
	s_add_u32 s56, s52, 0x30000
	s_addc_u32 s57, s53, 0
	global_load_dword v217, v133, s[56:57]
	global_load_dword v218, v133, s[56:57] offset:128
	global_load_dword v219, v134, s[56:57]
	global_load_dword v220, v134, s[56:57] offset:128
	global_load_dword v221, v135, s[56:57]
	global_load_dword v222, v135, s[56:57] offset:128
	global_load_dword v223, v136, s[56:57]
	global_load_dword v224, v136, s[56:57] offset:128
	s_waitcnt vmcnt(16)
	v_fmac_f32_e32 v193, v114, v137
	v_fmac_f32_e32 v194, v98, v138
	v_fmac_f32_e32 v195, v115, v137
	v_fmac_f32_e32 v196, v99, v138
	v_fmac_f32_e32 v197, v116, v137
	v_fmac_f32_e32 v198, v100, v138
	v_fmac_f32_e32 v199, v117, v137
	v_fmac_f32_e32 v200, v101, v138
	v_fmac_f32_e32 v201, v118, v137
	v_fmac_f32_e32 v202, v102, v138
	v_fmac_f32_e32 v203, v119, v137
	v_fmac_f32_e32 v204, v103, v138
	v_fmac_f32_e32 v205, v120, v137
	v_fmac_f32_e32 v206, v104, v138
	v_fmac_f32_e32 v207, v121, v137
	v_fmac_f32_e32 v208, v105, v138
	s_add_u32 s56, s52, 0x40000
	s_addc_u32 s57, s53, 0
	global_load_dword v225, v133, s[56:57]
	global_load_dword v226, v133, s[56:57] offset:128
	global_load_dword v227, v134, s[56:57]
	global_load_dword v228, v134, s[56:57] offset:128
	global_load_dword v229, v135, s[56:57]
	global_load_dword v230, v135, s[56:57] offset:128
	global_load_dword v231, v136, s[56:57]
	global_load_dword v237, v136, s[56:57] offset:128
	s_add_u32 s56, s52, 0x50000
	s_addc_u32 s57, s53, 0
	global_load_dword v238, v133, s[56:57]
	global_load_dword v239, v133, s[56:57] offset:128
	global_load_dword v240, v134, s[56:57]
	global_load_dword v241, v134, s[56:57] offset:128
	global_load_dword v242, v135, s[56:57]
	global_load_dword v243, v135, s[56:57] offset:128
	global_load_dword v244, v136, s[56:57]
	global_load_dword v245, v136, s[56:57] offset:128
	s_add_u32 s58, s54, 0x0
	s_addc_u32 s59, s55, 0
	global_store_dword v133, v193, s[58:59]
	global_store_dword v133, v194, s[58:59] offset:128
	global_store_dword v134, v195, s[58:59]
	global_store_dword v134, v196, s[58:59] offset:128
	global_store_dword v135, v197, s[58:59]
	global_store_dword v135, v198, s[58:59] offset:128
	global_store_dword v136, v199, s[58:59]
	global_store_dword v136, v200, s[58:59] offset:128
	s_add_u32 s58, s54, 0x10000
	s_addc_u32 s59, s55, 0
	global_store_dword v133, v201, s[58:59]
	global_store_dword v133, v202, s[58:59] offset:128
	global_store_dword v134, v203, s[58:59]
	global_store_dword v134, v204, s[58:59] offset:128
	global_store_dword v135, v205, s[58:59]
	global_store_dword v135, v206, s[58:59] offset:128
	global_store_dword v136, v207, s[58:59]
	global_store_dword v136, v208, s[58:59] offset:128
	s_waitcnt vmcnt(32)
; DI int tid512() { int t = threadIdx.x; asm volatile("" : "+v"(t)); return t; }
; DI void outproj256(const Params& p, int layer, char* smem) {
;     ...
;     const int t = tid512(), lane = t & 63, w = t >> 6, wm = w >> 2, wn = w & 3, r = lane & 31, h = lane >> 5;
; #pragma unroll
;     for (int mi = 0; mi < 4; ++mi)
; #pragma unroll
;       for (int ni = 0; ni < 2; ++ni) {
;         const int col = tn * 256 + 64 * wn + 32 * ni + r;
;         const float gg = g1[col];
; #pragma unroll
;         for (int reg = 0; reg < 16; ++reg) {
;           const int row = 256 + tm * 256 + 128 * wm + 32 * mi + (reg & 3) + 8 * (reg >> 2) + 4 * h;
;           const float res = (layer == 0) ? __builtin_nontemporal_load(p.x + (size_t)(row - 256) * DM + col) : X[(size_t)row * DM + col];
;           X[(size_t)row * DM + col] = res + gg * acc[mi][ni][reg];
;         }
;       }
	v_fmac_f32_e32 v209, v122, v137
	v_fmac_f32_e32 v210, v106, v138
	v_fmac_f32_e32 v211, v123, v137
	v_fmac_f32_e32 v212, v107, v138
	v_fmac_f32_e32 v213, v124, v137
	v_fmac_f32_e32 v214, v108, v138
	v_fmac_f32_e32 v215, v125, v137
	v_fmac_f32_e32 v216, v109, v138
	v_fmac_f32_e32 v217, v126, v137
	v_fmac_f32_e32 v218, v110, v138
	v_fmac_f32_e32 v219, v127, v137
	v_fmac_f32_e32 v220, v111, v138
	v_fmac_f32_e32 v221, v128, v137
	v_fmac_f32_e32 v222, v112, v138
	v_fmac_f32_e32 v223, v129, v137
	v_fmac_f32_e32 v224, v113, v138
	s_add_u32 s56, s52, 0x60000
	s_addc_u32 s57, s53, 0
	global_load_dword v193, v133, s[56:57]
	global_load_dword v194, v133, s[56:57] offset:128
	global_load_dword v195, v134, s[56:57]
	global_load_dword v196, v134, s[56:57] offset:128
	global_load_dword v197, v135, s[56:57]
	global_load_dword v198, v135, s[56:57] offset:128
	global_load_dword v199, v136, s[56:57]
	global_load_dword v200, v136, s[56:57] offset:128
	s_add_u32 s56, s52, 0x70000
	s_addc_u32 s57, s53, 0
	global_load_dword v201, v133, s[56:57]
	global_load_dword v202, v133, s[56:57] offset:128
	global_load_dword v203, v134, s[56:57]
	global_load_dword v204, v134, s[56:57] offset:128
	global_load_dword v205, v135, s[56:57]
	global_load_dword v206, v135, s[56:57] offset:128
	global_load_dword v207, v136, s[56:57]
	global_load_dword v208, v136, s[56:57] offset:128
	s_add_u32 s58, s54, 0x20000
	s_addc_u32 s59, s55, 0
	global_store_dword v133, v209, s[58:59]
	global_store_dword v133, v210, s[58:59] offset:128
	global_store_dword v134, v211, s[58:59]
	global_store_dword v134, v212, s[58:59] offset:128
	global_store_dword v135, v213, s[58:59]
	global_store_dword v135, v214, s[58:59] offset:128
	global_store_dword v136, v215, s[58:59]
	global_store_dword v136, v216, s[58:59] offset:128
	s_add_u32 s58, s54, 0x30000
	s_addc_u32 s59, s55, 0
	global_store_dword v133, v217, s[58:59]
	global_store_dword v133, v218, s[58:59] offset:128
	global_store_dword v134, v219, s[58:59]
	global_store_dword v134, v220, s[58:59] offset:128
	global_store_dword v135, v221, s[58:59]
	global_store_dword v135, v222, s[58:59] offset:128
	global_store_dword v136, v223, s[58:59]
	global_store_dword v136, v224, s[58:59] offset:128
	s_waitcnt vmcnt(48)
	v_fmac_f32_e32 v225, v82, v137
	v_fmac_f32_e32 v226, v66, v138
	v_fmac_f32_e32 v227, v83, v137
	v_fmac_f32_e32 v228, v67, v138
	v_fmac_f32_e32 v229, v84, v137
	v_fmac_f32_e32 v230, v68, v138
	v_fmac_f32_e32 v231, v85, v137
	v_fmac_f32_e32 v237, v69, v138
	v_fmac_f32_e32 v238, v86, v137
	v_fmac_f32_e32 v239, v70, v138
	v_fmac_f32_e32 v240, v87, v137
	v_fmac_f32_e32 v241, v71, v138
	v_fmac_f32_e32 v242, v88, v137
	v_fmac_f32_e32 v243, v72, v138
	v_fmac_f32_e32 v244, v89, v137
	v_fmac_f32_e32 v245, v73, v138
	s_add_u32 s56, s52, 0x80000
	s_addc_u32 s57, s53, 0
	global_load_dword v209, v133, s[56:57]
	global_load_dword v210, v133, s[56:57] offset:128
	global_load_dword v211, v134, s[56:57]
	global_load_dword v212, v134, s[56:57] offset:128
	global_load_dword v213, v135, s[56:57]
	global_load_dword v214, v135, s[56:57] offset:128
	global_load_dword v215, v136, s[56:57]
	global_load_dword v216, v136, s[56:57] offset:128
	s_add_u32 s56, s52, 0x90000
	s_addc_u32 s57, s53, 0
	global_load_dword v217, v133, s[56:57]
	global_load_dword v218, v133, s[56:57] offset:128
	global_load_dword v219, v134, s[56:57]
	global_load_dword v220, v134, s[56:57] offset:128
	global_load_dword v221, v135, s[56:57]
	global_load_dword v222, v135, s[56:57] offset:128
	global_load_dword v223, v136, s[56:57]
	global_load_dword v224, v136, s[56:57] offset:128
	s_add_u32 s58, s54, 0x40000
	s_addc_u32 s59, s55, 0
	global_store_dword v133, v225, s[58:59]
	global_store_dword v133, v226, s[58:59] offset:128
	global_store_dword v134, v227, s[58:59]
	global_store_dword v134, v228, s[58:59] offset:128
	global_store_dword v135, v229, s[58:59]
	global_store_dword v135, v230, s[58:59] offset:128
	global_store_dword v136, v231, s[58:59]
	global_store_dword v136, v237, s[58:59] offset:128
	s_add_u32 s58, s54, 0x50000
	s_addc_u32 s59, s55, 0
	global_store_dword v133, v238, s[58:59]
	global_store_dword v133, v239, s[58:59] offset:128
	global_store_dword v134, v240, s[58:59]
	global_store_dword v134, v241, s[58:59] offset:128
	global_store_dword v135, v242, s[58:59]
	global_store_dword v135, v243, s[58:59] offset:128
	global_store_dword v136, v244, s[58:59]
	global_store_dword v136, v245, s[58:59] offset:128
	s_waitcnt vmcnt(48)
	v_fmac_f32_e32 v193, v90, v137
	v_fmac_f32_e32 v194, v74, v138
	v_fmac_f32_e32 v195, v91, v137
	v_fmac_f32_e32 v196, v75, v138
	v_fmac_f32_e32 v197, v92, v137
	v_fmac_f32_e32 v198, v76, v138
	v_fmac_f32_e32 v199, v93, v137
	v_fmac_f32_e32 v200, v77, v138
	v_fmac_f32_e32 v201, v94, v137
	v_fmac_f32_e32 v202, v78, v138
	v_fmac_f32_e32 v203, v95, v137
	v_fmac_f32_e32 v204, v79, v138
	v_fmac_f32_e32 v205, v96, v137
	v_fmac_f32_e32 v206, v80, v138
	v_fmac_f32_e32 v207, v97, v137
	v_fmac_f32_e32 v208, v81, v138
	s_add_u32 s56, s52, 0xa0000
	s_addc_u32 s57, s53, 0
	global_load_dword v225, v133, s[56:57]
	global_load_dword v226, v133, s[56:57] offset:128
	global_load_dword v227, v134, s[56:57]
	global_load_dword v228, v134, s[56:57] offset:128
	global_load_dword v229, v135, s[56:57]
	global_load_dword v230, v135, s[56:57] offset:128
	global_load_dword v231, v136, s[56:57]
	global_load_dword v237, v136, s[56:57] offset:128
	s_add_u32 s56, s52, 0xb0000
	s_addc_u32 s57, s53, 0
	global_load_dword v238, v133, s[56:57]
	global_load_dword v239, v133, s[56:57] offset:128
	global_load_dword v240, v134, s[56:57]
	global_load_dword v241, v134, s[56:57] offset:128
	global_load_dword v242, v135, s[56:57]
	global_load_dword v243, v135, s[56:57] offset:128
	global_load_dword v244, v136, s[56:57]
	global_load_dword v245, v136, s[56:57] offset:128
	s_add_u32 s58, s54, 0x60000
	s_addc_u32 s59, s55, 0
	global_store_dword v133, v193, s[58:59]
	global_store_dword v133, v194, s[58:59] offset:128
	global_store_dword v134, v195, s[58:59]
	global_store_dword v134, v196, s[58:59] offset:128
	global_store_dword v135, v197, s[58:59]
	global_store_dword v135, v198, s[58:59] offset:128
	global_store_dword v136, v199, s[58:59]
	global_store_dword v136, v200, s[58:59] offset:128
	s_add_u32 s58, s54, 0x70000
	s_addc_u32 s59, s55, 0
	global_store_dword v133, v201, s[58:59]
	global_store_dword v133, v202, s[58:59] offset:128
	global_store_dword v134, v203, s[58:59]
	global_store_dword v134, v204, s[58:59] offset:128
	global_store_dword v135, v205, s[58:59]
	global_store_dword v135, v206, s[58:59] offset:128
	global_store_dword v136, v207, s[58:59]
	global_store_dword v136, v208, s[58:59] offset:128
	s_waitcnt vmcnt(48)
; DI int tid512() { int t = threadIdx.x; asm volatile("" : "+v"(t)); return t; }
; DI void outproj256(const Params& p, int layer, char* smem) {
;     ...
;     const int t = tid512(), lane = t & 63, w = t >> 6, wm = w >> 2, wn = w & 3, r = lane & 31, h = lane >> 5;
; #pragma unroll
;     for (int mi = 0; mi < 4; ++mi)
; #pragma unroll
;       for (int ni = 0; ni < 2; ++ni) {
;         const int col = tn * 256 + 64 * wn + 32 * ni + r;
;         const float gg = g1[col];
; #pragma unroll
;         for (int reg = 0; reg < 16; ++reg) {
;           const int row = 256 + tm * 256 + 128 * wm + 32 * mi + (reg & 3) + 8 * (reg >> 2) + 4 * h;
;           const float res = (layer == 0) ? __builtin_nontemporal_load(p.x + (size_t)(row - 256) * DM + col) : X[(size_t)row * DM + col];
;           X[(size_t)row * DM + col] = res + gg * acc[mi][ni][reg];
;         }
;       }
	v_fmac_f32_e32 v209, v50, v137
	v_fmac_f32_e32 v210, v34, v138
	v_fmac_f32_e32 v211, v51, v137
	v_fmac_f32_e32 v212, v35, v138
	v_fmac_f32_e32 v213, v52, v137
	v_fmac_f32_e32 v214, v36, v138
	v_fmac_f32_e32 v215, v53, v137
	v_fmac_f32_e32 v216, v37, v138
	v_fmac_f32_e32 v217, v54, v137
	v_fmac_f32_e32 v218, v38, v138
	v_fmac_f32_e32 v219, v55, v137
	v_fmac_f32_e32 v220, v39, v138
	v_fmac_f32_e32 v221, v56, v137
	v_fmac_f32_e32 v222, v40, v138
	v_fmac_f32_e32 v223, v57, v137
	v_fmac_f32_e32 v224, v41, v138
	s_add_u32 s56, s52, 0xc0000
	s_addc_u32 s57, s53, 0
	global_load_dword v193, v133, s[56:57]
	global_load_dword v194, v133, s[56:57] offset:128
	global_load_dword v195, v134, s[56:57]
	global_load_dword v196, v134, s[56:57] offset:128
	global_load_dword v197, v135, s[56:57]
	global_load_dword v198, v135, s[56:57] offset:128
	global_load_dword v199, v136, s[56:57]
	global_load_dword v200, v136, s[56:57] offset:128
	s_add_u32 s56, s52, 0xd0000
	s_addc_u32 s57, s53, 0
	global_load_dword v201, v133, s[56:57]
	global_load_dword v202, v133, s[56:57] offset:128
	global_load_dword v203, v134, s[56:57]
	global_load_dword v204, v134, s[56:57] offset:128
	global_load_dword v205, v135, s[56:57]
	global_load_dword v206, v135, s[56:57] offset:128
	global_load_dword v207, v136, s[56:57]
	global_load_dword v208, v136, s[56:57] offset:128
	s_add_u32 s58, s54, 0x80000
	s_addc_u32 s59, s55, 0
	global_store_dword v133, v209, s[58:59]
	global_store_dword v133, v210, s[58:59] offset:128
	global_store_dword v134, v211, s[58:59]
	global_store_dword v134, v212, s[58:59] offset:128
	global_store_dword v135, v213, s[58:59]
	global_store_dword v135, v214, s[58:59] offset:128
	global_store_dword v136, v215, s[58:59]
	global_store_dword v136, v216, s[58:59] offset:128
	s_add_u32 s58, s54, 0x90000
	s_addc_u32 s59, s55, 0
	global_store_dword v133, v217, s[58:59]
	global_store_dword v133, v218, s[58:59] offset:128
	global_store_dword v134, v219, s[58:59]
	global_store_dword v134, v220, s[58:59] offset:128
	global_store_dword v135, v221, s[58:59]
	global_store_dword v135, v222, s[58:59] offset:128
	global_store_dword v136, v223, s[58:59]
	global_store_dword v136, v224, s[58:59] offset:128
	s_waitcnt vmcnt(48)
	v_fmac_f32_e32 v225, v58, v137
	v_fmac_f32_e32 v226, v42, v138
	v_fmac_f32_e32 v227, v59, v137
	v_fmac_f32_e32 v228, v43, v138
	v_fmac_f32_e32 v229, v60, v137
	v_fmac_f32_e32 v230, v44, v138
	v_fmac_f32_e32 v231, v61, v137
	v_fmac_f32_e32 v237, v45, v138
	v_fmac_f32_e32 v238, v62, v137
	v_fmac_f32_e32 v239, v46, v138
	v_fmac_f32_e32 v240, v63, v137
	v_fmac_f32_e32 v241, v47, v138
	v_fmac_f32_e32 v242, v64, v137
	v_fmac_f32_e32 v243, v48, v138
	v_fmac_f32_e32 v244, v65, v137
	v_fmac_f32_e32 v245, v49, v138
	s_add_u32 s56, s52, 0xe0000
	s_addc_u32 s57, s53, 0
	global_load_dword v209, v133, s[56:57]
	global_load_dword v210, v133, s[56:57] offset:128
	global_load_dword v211, v134, s[56:57]
	global_load_dword v212, v134, s[56:57] offset:128
	global_load_dword v213, v135, s[56:57]
	global_load_dword v214, v135, s[56:57] offset:128
	global_load_dword v215, v136, s[56:57]
	global_load_dword v216, v136, s[56:57] offset:128
	s_add_u32 s56, s52, 0xf0000
	s_addc_u32 s57, s53, 0
	global_load_dword v217, v133, s[56:57]
	global_load_dword v218, v133, s[56:57] offset:128
	global_load_dword v219, v134, s[56:57]
	global_load_dword v220, v134, s[56:57] offset:128
	global_load_dword v221, v135, s[56:57]
	global_load_dword v222, v135, s[56:57] offset:128
	global_load_dword v223, v136, s[56:57]
	global_load_dword v224, v136, s[56:57] offset:128
	s_add_u32 s58, s54, 0xa0000
	s_addc_u32 s59, s55, 0
	global_store_dword v133, v225, s[58:59]
	global_store_dword v133, v226, s[58:59] offset:128
	global_store_dword v134, v227, s[58:59]
	global_store_dword v134, v228, s[58:59] offset:128
	global_store_dword v135, v229, s[58:59]
	global_store_dword v135, v230, s[58:59] offset:128
	global_store_dword v136, v231, s[58:59]
	global_store_dword v136, v237, s[58:59] offset:128
	s_add_u32 s58, s54, 0xb0000
	s_addc_u32 s59, s55, 0
	global_store_dword v133, v238, s[58:59]
	global_store_dword v133, v239, s[58:59] offset:128
	global_store_dword v134, v240, s[58:59]
	global_store_dword v134, v241, s[58:59] offset:128
	global_store_dword v135, v242, s[58:59]
	global_store_dword v135, v243, s[58:59] offset:128
	global_store_dword v136, v244, s[58:59]
	global_store_dword v136, v245, s[58:59] offset:128
	s_waitcnt vmcnt(48)
; DI int tid512() { int t = threadIdx.x; asm volatile("" : "+v"(t)); return t; }
; DI void outproj256(const Params& p, int layer, char* smem) {
;     ...
;     const int t = tid512(), lane = t & 63, w = t >> 6, wm = w >> 2, wn = w & 3, r = lane & 31, h = lane >> 5;
; #pragma unroll
;     for (int mi = 0; mi < 4; ++mi)
; #pragma unroll
;       for (int ni = 0; ni < 2; ++ni) {
;         const int col = tn * 256 + 64 * wn + 32 * ni + r;
;         const float gg = g1[col];
; #pragma unroll
;         for (int reg = 0; reg < 16; ++reg) {
;           const int row = 256 + tm * 256 + 128 * wm + 32 * mi + (reg & 3) + 8 * (reg >> 2) + 4 * h;
;           const float res = (layer == 0) ? __builtin_nontemporal_load(p.x + (size_t)(row - 256) * DM + col) : X[(size_t)row * DM + col];
;           X[(size_t)row * DM + col] = res + gg * acc[mi][ni][reg];
;         }
;       }
	v_fmac_f32_e32 v193, v18, v137
	v_fmac_f32_e32 v194, v2, v138
	v_fmac_f32_e32 v195, v19, v137
	v_fmac_f32_e32 v196, v3, v138
	v_fmac_f32_e32 v197, v20, v137
	v_fmac_f32_e32 v198, v4, v138
	v_fmac_f32_e32 v199, v21, v137
	v_fmac_f32_e32 v200, v5, v138
	v_fmac_f32_e32 v201, v22, v137
	v_fmac_f32_e32 v202, v6, v138
	v_fmac_f32_e32 v203, v23, v137
	v_fmac_f32_e32 v204, v7, v138
	v_fmac_f32_e32 v205, v24, v137
	v_fmac_f32_e32 v206, v8, v138
	v_fmac_f32_e32 v207, v25, v137
	v_fmac_f32_e32 v208, v9, v138
	s_add_u32 s58, s54, 0xc0000
	s_addc_u32 s59, s55, 0
	global_store_dword v133, v193, s[58:59]
	global_store_dword v133, v194, s[58:59] offset:128
	global_store_dword v134, v195, s[58:59]
	global_store_dword v134, v196, s[58:59] offset:128
	global_store_dword v135, v197, s[58:59]
	global_store_dword v135, v198, s[58:59] offset:128
	global_store_dword v136, v199, s[58:59]
	global_store_dword v136, v200, s[58:59] offset:128
	s_add_u32 s58, s54, 0xd0000
	s_addc_u32 s59, s55, 0
	global_store_dword v133, v201, s[58:59]
	global_store_dword v133, v202, s[58:59] offset:128
	global_store_dword v134, v203, s[58:59]
	global_store_dword v134, v204, s[58:59] offset:128
	global_store_dword v135, v205, s[58:59]
	global_store_dword v135, v206, s[58:59] offset:128
	global_store_dword v136, v207, s[58:59]
	global_store_dword v136, v208, s[58:59] offset:128
	s_waitcnt vmcnt(32)
	v_fmac_f32_e32 v209, v26, v137
	v_fmac_f32_e32 v210, v10, v138
	v_fmac_f32_e32 v211, v27, v137
	v_fmac_f32_e32 v212, v11, v138
	v_fmac_f32_e32 v213, v28, v137
	v_fmac_f32_e32 v214, v12, v138
	v_fmac_f32_e32 v215, v29, v137
	v_fmac_f32_e32 v216, v13, v138
	v_fmac_f32_e32 v217, v30, v137
	v_fmac_f32_e32 v218, v14, v138
	v_fmac_f32_e32 v219, v31, v137
	v_fmac_f32_e32 v220, v15, v138
	v_fmac_f32_e32 v221, v32, v137
	v_fmac_f32_e32 v222, v16, v138
	v_fmac_f32_e32 v223, v33, v137
	v_fmac_f32_e32 v224, v17, v138
	s_add_u32 s58, s54, 0xe0000
	s_addc_u32 s59, s55, 0
	global_store_dword v133, v209, s[58:59]
	global_store_dword v133, v210, s[58:59] offset:128
	global_store_dword v134, v211, s[58:59]
	global_store_dword v134, v212, s[58:59] offset:128
	global_store_dword v135, v213, s[58:59]
	global_store_dword v135, v214, s[58:59] offset:128
	global_store_dword v136, v215, s[58:59]
	global_store_dword v136, v216, s[58:59] offset:128
	s_add_u32 s58, s54, 0xf0000
	s_addc_u32 s59, s55, 0
	global_store_dword v133, v217, s[58:59]
	global_store_dword v133, v218, s[58:59] offset:128
	global_store_dword v134, v219, s[58:59]
	global_store_dword v134, v220, s[58:59] offset:128
	global_store_dword v135, v221, s[58:59]
	global_store_dword v135, v222, s[58:59] offset:128
	global_store_dword v136, v223, s[58:59]
	global_store_dword v136, v224, s[58:59] offset:128
	s_branch .LBB0_915

; DI int tid512() { int t = threadIdx.x; asm volatile("" : "+v"(t)); return t; }
; DI void down256(const Params& p, int layer, char* smem) {
;     ...
;     const int t = tid512(), lane = t & 63, w = t >> 6, wm = w >> 2, wn = w & 3, r = lane & 31, h = lane >> 5;
; #pragma unroll
;     for (int mi = 0; mi < 4; ++mi)
; #pragma unroll
;       for (int ni = 0; ni < 2; ++ni) {
;         const int col = tn * 256 + 64 * wn + 32 * ni + r;
;         const float gg = g2[col];
; #pragma unroll
;         for (int reg = 0; reg < 16; ++reg) {
;           const int row = 256 + tm * 256 + 128 * wm + 32 * mi + (reg & 3) + 8 * (reg >> 2) + 4 * h;
;           X[(size_t)row * DM + col] += gg * acc[mi][ni][reg];
;         }
;       }
.LBB0_1646:
	s_waitcnt vmcnt(0)
	v_and_b32_e32 v130, 0xdf, v0
	v_or_b32_e32 v130, s12, v130
	v_lshlrev_b32_e32 v130, 2, v130
	global_load_dword v137, v130, s[0:1]
	global_load_dword v138, v130, s[0:1] offset:128
	v_ashrrev_i32_e32 v131, 1, v0
	v_and_b32_e32 v131, 0xffffff80, v131
	v_add_u32_e32 v131, s11, v131
	v_lshrrev_b32_e32 v132, 3, v0
	v_and_or_b32 v131, v132, 4, v131
	v_lshl_add_u32 v133, v131, 13, v130
	v_add_u32_e32 v134, 0x2000, v133
	v_add_u32_e32 v135, 0x4000, v133
	v_add_u32_e32 v136, 0x6000, v133
	s_mov_b64 s[52:53], s[90:91]
	s_mov_b64 s[54:55], s[90:91]
	s_add_i32 s10, s10, 1
	s_add_u32 s56, s52, 0x0
	s_addc_u32 s57, s53, 0
	global_load_dword v193, v133, s[56:57]
	global_load_dword v194, v133, s[56:57] offset:128
	global_load_dword v195, v134, s[56:57]
	global_load_dword v196, v134, s[56:57] offset:128
	global_load_dword v197, v135, s[56:57]
	global_load_dword v198, v135, s[56:57] offset:128
	global_load_dword v199, v136, s[56:57]
	global_load_dword v200, v136, s[56:57] offset:128
	s_add_u32 s56, s52, 0x10000
	s_addc_u32 s57, s53, 0
	global_load_dword v201, v133, s[56:57]
	global_load_dword v202, v133, s[56:57] offset:128
	global_load_dword v203, v134, s[56:57]
	global_load_dword v204, v134, s[56:57] offset:128
	global_load_dword v205, v135, s[56:57]
	global_load_dword v206, v135, s[56:57] offset:128
	global_load_dword v207, v136, s[56:57]
	global_load_dword v208, v136, s[56:57] offset:128
	s_add_u32 s56, s52, 0x20000
	s_addc_u32 s57, s53, 0
	global_load_dword v209, v133, s[56:57]
	global_load_dword v210, v133, s[56:57] offset:128
	global_load_dword v211, v134, s[56:57]
	global_load_dword v212, v134, s[56:57] offset:128
	global_load_dword v213, v135, s[56:57]
	global_load_dword v214, v135, s[56:57] offset:128
	global_load_dword v215, v136, s[56:57]
	global_load_dword v216, v136, s[56:57] offset:128
	s_add_u32 s56, s52, 0x30000
	s_addc_u32 s57, s53, 0
	global_load_dword v217, v133, s[56:57]
	global_load_dword v218, v133, s[56:57] offset:128
	global_load_dword v219, v134, s[56:57]
	global_load_dword v220, v134, s[56:57] offset:128
	global_load_dword v221, v135, s[56:57]
	global_load_dword v222, v135, s[56:57] offset:128
	global_load_dword v223, v136, s[56:57]
	global_load_dword v224, v136, s[56:57] offset:128
	s_waitcnt vmcnt(16)
	v_fmac_f32_e32 v193, v114, v137
	v_fmac_f32_e32 v194, v98, v138
	v_fmac_f32_e32 v195, v115, v137
	v_fmac_f32_e32 v196, v99, v138
	v_fmac_f32_e32 v197, v116, v137
	v_fmac_f32_e32 v198, v100, v138
	v_fmac_f32_e32 v199, v117, v137
	v_fmac_f32_e32 v200, v101, v138
	v_fmac_f32_e32 v201, v118, v137
	v_fmac_f32_e32 v202, v102, v138
	v_fmac_f32_e32 v203, v119, v137
	v_fmac_f32_e32 v204, v103, v138
	v_fmac_f32_e32 v205, v120, v137
	v_fmac_f32_e32 v206, v104, v138
	v_fmac_f32_e32 v207, v121, v137
	v_fmac_f32_e32 v208, v105, v138
	s_add_u32 s56, s52, 0x40000
	s_addc_u32 s57, s53, 0
	global_load_dword v225, v133, s[56:57]
	global_load_dword v226, v133, s[56:57] offset:128
	global_load_dword v227, v134, s[56:57]
	global_load_dword v228, v134, s[56:57] offset:128
	global_load_dword v229, v135, s[56:57]
	global_load_dword v230, v135, s[56:57] offset:128
	global_load_dword v231, v136, s[56:57]
	global_load_dword v237, v136, s[56:57] offset:128
	s_add_u32 s56, s52, 0x50000
	s_addc_u32 s57, s53, 0
	global_load_dword v238, v133, s[56:57]
	global_load_dword v239, v133, s[56:57] offset:128
	global_load_dword v240, v134, s[56:57]
	global_load_dword v241, v134, s[56:57] offset:128
	global_load_dword v242, v135, s[56:57]
	global_load_dword v243, v135, s[56:57] offset:128
	global_load_dword v244, v136, s[56:57]
	global_load_dword v245, v136, s[56:57] offset:128
	s_add_u32 s58, s54, 0x0
	s_addc_u32 s59, s55, 0
	global_store_dword v133, v193, s[58:59]
	global_store_dword v133, v194, s[58:59] offset:128
	global_store_dword v134, v195, s[58:59]
	global_store_dword v134, v196, s[58:59] offset:128
	global_store_dword v135, v197, s[58:59]
	global_store_dword v135, v198, s[58:59] offset:128
	global_store_dword v136, v199, s[58:59]
	global_store_dword v136, v200, s[58:59] offset:128
	s_add_u32 s58, s54, 0x10000
	s_addc_u32 s59, s55, 0
	global_store_dword v133, v201, s[58:59]
	global_store_dword v133, v202, s[58:59] offset:128
	global_store_dword v134, v203, s[58:59]
	global_store_dword v134, v204, s[58:59] offset:128
	global_store_dword v135, v205, s[58:59]
	global_store_dword v135, v206, s[58:59] offset:128
	global_store_dword v136, v207, s[58:59]
	global_store_dword v136, v208, s[58:59] offset:128
	s_waitcnt vmcnt(32)
	v_fmac_f32_e32 v209, v122, v137
	v_fmac_f32_e32 v210, v106, v138
	v_fmac_f32_e32 v211, v123, v137
	v_fmac_f32_e32 v212, v107, v138
	v_fmac_f32_e32 v213, v124, v137
	v_fmac_f32_e32 v214, v108, v138
	v_fmac_f32_e32 v215, v125, v137
	v_fmac_f32_e32 v216, v109, v138
	v_fmac_f32_e32 v217, v126, v137
	v_fmac_f32_e32 v218, v110, v138
	v_fmac_f32_e32 v219, v127, v137
	v_fmac_f32_e32 v220, v111, v138
	v_fmac_f32_e32 v221, v128, v137
	v_fmac_f32_e32 v222, v112, v138
	v_fmac_f32_e32 v223, v129, v137
	v_fmac_f32_e32 v224, v113, v138
	s_add_u32 s56, s52, 0x60000
	s_addc_u32 s57, s53, 0
	global_load_dword v193, v133, s[56:57]
	global_load_dword v194, v133, s[56:57] offset:128
	global_load_dword v195, v134, s[56:57]
	global_load_dword v196, v134, s[56:57] offset:128
	global_load_dword v197, v135, s[56:57]
	global_load_dword v198, v135, s[56:57] offset:128
	global_load_dword v199, v136, s[56:57]
	global_load_dword v200, v136, s[56:57] offset:128
	s_add_u32 s56, s52, 0x70000
	s_addc_u32 s57, s53, 0
	global_load_dword v201, v133, s[56:57]
	global_load_dword v202, v133, s[56:57] offset:128
	global_load_dword v203, v134, s[56:57]
	global_load_dword v204, v134, s[56:57] offset:128
	global_load_dword v205, v135, s[56:57]
	global_load_dword v206, v135, s[56:57] offset:128
	global_load_dword v207, v136, s[56:57]
	global_load_dword v208, v136, s[56:57] offset:128
	s_add_u32 s58, s54, 0x20000
	s_addc_u32 s59, s55, 0
	global_store_dword v133, v209, s[58:59]
	global_store_dword v133, v210, s[58:59] offset:128
	global_store_dword v134, v211, s[58:59]
	global_store_dword v134, v212, s[58:59] offset:128
	global_store_dword v135, v213, s[58:59]
	global_store_dword v135, v214, s[58:59] offset:128
	global_store_dword v136, v215, s[58:59]
	global_store_dword v136, v216, s[58:59] offset:128
	s_add_u32 s58, s54, 0x30000
	s_addc_u32 s59, s55, 0
	global_store_dword v133, v217, s[58:59]
	global_store_dword v133, v218, s[58:59] offset:128
	global_store_dword v134, v219, s[58:59]
	global_store_dword v134, v220, s[58:59] offset:128
	global_store_dword v135, v221, s[58:59]
	global_store_dword v135, v222, s[58:59] offset:128
	global_store_dword v136, v223, s[58:59]
	global_store_dword v136, v224, s[58:59] offset:128
	s_waitcnt vmcnt(48)
; DI int tid512() { int t = threadIdx.x; asm volatile("" : "+v"(t)); return t; }
; DI void down256(const Params& p, int layer, char* smem) {
;     ...
;     const int t = tid512(), lane = t & 63, w = t >> 6, wm = w >> 2, wn = w & 3, r = lane & 31, h = lane >> 5;
; #pragma unroll
;     for (int mi = 0; mi < 4; ++mi)
; #pragma unroll
;       for (int ni = 0; ni < 2; ++ni) {
;         const int col = tn * 256 + 64 * wn + 32 * ni + r;
;         const float gg = g2[col];
; #pragma unroll
;         for (int reg = 0; reg < 16; ++reg) {
;           const int row = 256 + tm * 256 + 128 * wm + 32 * mi + (reg & 3) + 8 * (reg >> 2) + 4 * h;
;           X[(size_t)row * DM + col] += gg * acc[mi][ni][reg];
;         }
;       }
	v_fmac_f32_e32 v225, v82, v137
	v_fmac_f32_e32 v226, v66, v138
	v_fmac_f32_e32 v227, v83, v137
	v_fmac_f32_e32 v228, v67, v138
	v_fmac_f32_e32 v229, v84, v137
	v_fmac_f32_e32 v230, v68, v138
	v_fmac_f32_e32 v231, v85, v137
	v_fmac_f32_e32 v237, v69, v138
	v_fmac_f32_e32 v238, v86, v137
	v_fmac_f32_e32 v239, v70, v138
	v_fmac_f32_e32 v240, v87, v137
	v_fmac_f32_e32 v241, v71, v138
	v_fmac_f32_e32 v242, v88, v137
	v_fmac_f32_e32 v243, v72, v138
	v_fmac_f32_e32 v244, v89, v137
	v_fmac_f32_e32 v245, v73, v138
	s_add_u32 s56, s52, 0x80000
	s_addc_u32 s57, s53, 0
	global_load_dword v209, v133, s[56:57]
	global_load_dword v210, v133, s[56:57] offset:128
	global_load_dword v211, v134, s[56:57]
	global_load_dword v212, v134, s[56:57] offset:128
	global_load_dword v213, v135, s[56:57]
	global_load_dword v214, v135, s[56:57] offset:128
	global_load_dword v215, v136, s[56:57]
	global_load_dword v216, v136, s[56:57] offset:128
	s_add_u32 s56, s52, 0x90000
	s_addc_u32 s57, s53, 0
	global_load_dword v217, v133, s[56:57]
	global_load_dword v218, v133, s[56:57] offset:128
	global_load_dword v219, v134, s[56:57]
	global_load_dword v220, v134, s[56:57] offset:128
	global_load_dword v221, v135, s[56:57]
	global_load_dword v222, v135, s[56:57] offset:128
	global_load_dword v223, v136, s[56:57]
	global_load_dword v224, v136, s[56:57] offset:128
	s_add_u32 s58, s54, 0x40000
	s_addc_u32 s59, s55, 0
	global_store_dword v133, v225, s[58:59]
	global_store_dword v133, v226, s[58:59] offset:128
	global_store_dword v134, v227, s[58:59]
	global_store_dword v134, v228, s[58:59] offset:128
	global_store_dword v135, v229, s[58:59]
	global_store_dword v135, v230, s[58:59] offset:128
	global_store_dword v136, v231, s[58:59]
	global_store_dword v136, v237, s[58:59] offset:128
	s_add_u32 s58, s54, 0x50000
	s_addc_u32 s59, s55, 0
	global_store_dword v133, v238, s[58:59]
	global_store_dword v133, v239, s[58:59] offset:128
	global_store_dword v134, v240, s[58:59]
	global_store_dword v134, v241, s[58:59] offset:128
	global_store_dword v135, v242, s[58:59]
	global_store_dword v135, v243, s[58:59] offset:128
	global_store_dword v136, v244, s[58:59]
	global_store_dword v136, v245, s[58:59] offset:128
	s_waitcnt vmcnt(48)
	v_fmac_f32_e32 v193, v90, v137
	v_fmac_f32_e32 v194, v74, v138
	v_fmac_f32_e32 v195, v91, v137
	v_fmac_f32_e32 v196, v75, v138
	v_fmac_f32_e32 v197, v92, v137
	v_fmac_f32_e32 v198, v76, v138
	v_fmac_f32_e32 v199, v93, v137
	v_fmac_f32_e32 v200, v77, v138
	v_fmac_f32_e32 v201, v94, v137
	v_fmac_f32_e32 v202, v78, v138
	v_fmac_f32_e32 v203, v95, v137
	v_fmac_f32_e32 v204, v79, v138
	v_fmac_f32_e32 v205, v96, v137
	v_fmac_f32_e32 v206, v80, v138
	v_fmac_f32_e32 v207, v97, v137
	v_fmac_f32_e32 v208, v81, v138
	s_add_u32 s56, s52, 0xa0000
	s_addc_u32 s57, s53, 0
	global_load_dword v225, v133, s[56:57]
	global_load_dword v226, v133, s[56:57] offset:128
	global_load_dword v227, v134, s[56:57]
	global_load_dword v228, v134, s[56:57] offset:128
	global_load_dword v229, v135, s[56:57]
	global_load_dword v230, v135, s[56:57] offset:128
	global_load_dword v231, v136, s[56:57]
	global_load_dword v237, v136, s[56:57] offset:128
	s_add_u32 s56, s52, 0xb0000
	s_addc_u32 s57, s53, 0
	global_load_dword v238, v133, s[56:57]
	global_load_dword v239, v133, s[56:57] offset:128
	global_load_dword v240, v134, s[56:57]
	global_load_dword v241, v134, s[56:57] offset:128
	global_load_dword v242, v135, s[56:57]
	global_load_dword v243, v135, s[56:57] offset:128
	global_load_dword v244, v136, s[56:57]
	global_load_dword v245, v136, s[56:57] offset:128
	s_add_u32 s58, s54, 0x60000
	s_addc_u32 s59, s55, 0
	global_store_dword v133, v193, s[58:59]
	global_store_dword v133, v194, s[58:59] offset:128
	global_store_dword v134, v195, s[58:59]
	global_store_dword v134, v196, s[58:59] offset:128
	global_store_dword v135, v197, s[58:59]
	global_store_dword v135, v198, s[58:59] offset:128
	global_store_dword v136, v199, s[58:59]
	global_store_dword v136, v200, s[58:59] offset:128
	s_add_u32 s58, s54, 0x70000
	s_addc_u32 s59, s55, 0
	global_store_dword v133, v201, s[58:59]
	global_store_dword v133, v202, s[58:59] offset:128
	global_store_dword v134, v203, s[58:59]
	global_store_dword v134, v204, s[58:59] offset:128
	global_store_dword v135, v205, s[58:59]
	global_store_dword v135, v206, s[58:59] offset:128
	global_store_dword v136, v207, s[58:59]
	global_store_dword v136, v208, s[58:59] offset:128
	s_waitcnt vmcnt(48)
	v_fmac_f32_e32 v209, v50, v137
	v_fmac_f32_e32 v210, v34, v138
	v_fmac_f32_e32 v211, v51, v137
	v_fmac_f32_e32 v212, v35, v138
	v_fmac_f32_e32 v213, v52, v137
	v_fmac_f32_e32 v214, v36, v138
	v_fmac_f32_e32 v215, v53, v137
	v_fmac_f32_e32 v216, v37, v138
	v_fmac_f32_e32 v217, v54, v137
	v_fmac_f32_e32 v218, v38, v138
	v_fmac_f32_e32 v219, v55, v137
	v_fmac_f32_e32 v220, v39, v138
	v_fmac_f32_e32 v221, v56, v137
	v_fmac_f32_e32 v222, v40, v138
	v_fmac_f32_e32 v223, v57, v137
	v_fmac_f32_e32 v224, v41, v138
	s_add_u32 s56, s52, 0xc0000
	s_addc_u32 s57, s53, 0
	global_load_dword v193, v133, s[56:57]
	global_load_dword v194, v133, s[56:57] offset:128
	global_load_dword v195, v134, s[56:57]
	global_load_dword v196, v134, s[56:57] offset:128
	global_load_dword v197, v135, s[56:57]
	global_load_dword v198, v135, s[56:57] offset:128
	global_load_dword v199, v136, s[56:57]
	global_load_dword v200, v136, s[56:57] offset:128
	s_add_u32 s56, s52, 0xd0000
	s_addc_u32 s57, s53, 0
	global_load_dword v201, v133, s[56:57]
	global_load_dword v202, v133, s[56:57] offset:128
	global_load_dword v203, v134, s[56:57]
	global_load_dword v204, v134, s[56:57] offset:128
	global_load_dword v205, v135, s[56:57]
	global_load_dword v206, v135, s[56:57] offset:128
	global_load_dword v207, v136, s[56:57]
	global_load_dword v208, v136, s[56:57] offset:128
	s_add_u32 s58, s54, 0x80000
	s_addc_u32 s59, s55, 0
	global_store_dword v133, v209, s[58:59]
	global_store_dword v133, v210, s[58:59] offset:128
	global_store_dword v134, v211, s[58:59]
	global_store_dword v134, v212, s[58:59] offset:128
	global_store_dword v135, v213, s[58:59]
	global_store_dword v135, v214, s[58:59] offset:128
	global_store_dword v136, v215, s[58:59]
	global_store_dword v136, v216, s[58:59] offset:128
	s_add_u32 s58, s54, 0x90000
	s_addc_u32 s59, s55, 0
	global_store_dword v133, v217, s[58:59]
	global_store_dword v133, v218, s[58:59] offset:128
	global_store_dword v134, v219, s[58:59]
	global_store_dword v134, v220, s[58:59] offset:128
	global_store_dword v135, v221, s[58:59]
	global_store_dword v135, v222, s[58:59] offset:128
	global_store_dword v136, v223, s[58:59]
	global_store_dword v136, v224, s[58:59] offset:128
	s_waitcnt vmcnt(48)
; DI int tid512() { int t = threadIdx.x; asm volatile("" : "+v"(t)); return t; }
; DI void down256(const Params& p, int layer, char* smem) {
;     ...
;     const int t = tid512(), lane = t & 63, w = t >> 6, wm = w >> 2, wn = w & 3, r = lane & 31, h = lane >> 5;
; #pragma unroll
;     for (int mi = 0; mi < 4; ++mi)
; #pragma unroll
;       for (int ni = 0; ni < 2; ++ni) {
;         const int col = tn * 256 + 64 * wn + 32 * ni + r;
;         const float gg = g2[col];
; #pragma unroll
;         for (int reg = 0; reg < 16; ++reg) {
;           const int row = 256 + tm * 256 + 128 * wm + 32 * mi + (reg & 3) + 8 * (reg >> 2) + 4 * h;
;           X[(size_t)row * DM + col] += gg * acc[mi][ni][reg];
;         }
;       }
	v_fmac_f32_e32 v225, v58, v137
	v_fmac_f32_e32 v226, v42, v138
	v_fmac_f32_e32 v227, v59, v137
	v_fmac_f32_e32 v228, v43, v138
	v_fmac_f32_e32 v229, v60, v137
	v_fmac_f32_e32 v230, v44, v138
	v_fmac_f32_e32 v231, v61, v137
	v_fmac_f32_e32 v237, v45, v138
	v_fmac_f32_e32 v238, v62, v137
	v_fmac_f32_e32 v239, v46, v138
	v_fmac_f32_e32 v240, v63, v137
	v_fmac_f32_e32 v241, v47, v138
	v_fmac_f32_e32 v242, v64, v137
	v_fmac_f32_e32 v243, v48, v138
	v_fmac_f32_e32 v244, v65, v137
	v_fmac_f32_e32 v245, v49, v138
	s_add_u32 s56, s52, 0xe0000
	s_addc_u32 s57, s53, 0
	global_load_dword v209, v133, s[56:57]
	global_load_dword v210, v133, s[56:57] offset:128
	global_load_dword v211, v134, s[56:57]
	global_load_dword v212, v134, s[56:57] offset:128
	global_load_dword v213, v135, s[56:57]
	global_load_dword v214, v135, s[56:57] offset:128
	global_load_dword v215, v136, s[56:57]
	global_load_dword v216, v136, s[56:57] offset:128
	s_add_u32 s56, s52, 0xf0000
	s_addc_u32 s57, s53, 0
	global_load_dword v217, v133, s[56:57]
	global_load_dword v218, v133, s[56:57] offset:128
	global_load_dword v219, v134, s[56:57]
	global_load_dword v220, v134, s[56:57] offset:128
	global_load_dword v221, v135, s[56:57]
	global_load_dword v222, v135, s[56:57] offset:128
	global_load_dword v223, v136, s[56:57]
	global_load_dword v224, v136, s[56:57] offset:128
	s_add_u32 s58, s54, 0xa0000
	s_addc_u32 s59, s55, 0
	global_store_dword v133, v225, s[58:59]
	global_store_dword v133, v226, s[58:59] offset:128
	global_store_dword v134, v227, s[58:59]
	global_store_dword v134, v228, s[58:59] offset:128
	global_store_dword v135, v229, s[58:59]
	global_store_dword v135, v230, s[58:59] offset:128
	global_store_dword v136, v231, s[58:59]
	global_store_dword v136, v237, s[58:59] offset:128
	s_add_u32 s58, s54, 0xb0000
	s_addc_u32 s59, s55, 0
	global_store_dword v133, v238, s[58:59]
	global_store_dword v133, v239, s[58:59] offset:128
	global_store_dword v134, v240, s[58:59]
	global_store_dword v134, v241, s[58:59] offset:128
	global_store_dword v135, v242, s[58:59]
	global_store_dword v135, v243, s[58:59] offset:128
	global_store_dword v136, v244, s[58:59]
	global_store_dword v136, v245, s[58:59] offset:128
	s_waitcnt vmcnt(48)
	v_fmac_f32_e32 v193, v18, v137
	v_fmac_f32_e32 v194, v2, v138
	v_fmac_f32_e32 v195, v19, v137
	v_fmac_f32_e32 v196, v3, v138
	v_fmac_f32_e32 v197, v20, v137
	v_fmac_f32_e32 v198, v4, v138
	v_fmac_f32_e32 v199, v21, v137
	v_fmac_f32_e32 v200, v5, v138
	v_fmac_f32_e32 v201, v22, v137
	v_fmac_f32_e32 v202, v6, v138
	v_fmac_f32_e32 v203, v23, v137
	v_fmac_f32_e32 v204, v7, v138
	v_fmac_f32_e32 v205, v24, v137
	v_fmac_f32_e32 v206, v8, v138
	v_fmac_f32_e32 v207, v25, v137
	v_fmac_f32_e32 v208, v9, v138
	s_add_u32 s58, s54, 0xc0000
	s_addc_u32 s59, s55, 0
	global_store_dword v133, v193, s[58:59]
	global_store_dword v133, v194, s[58:59] offset:128
	global_store_dword v134, v195, s[58:59]
	global_store_dword v134, v196, s[58:59] offset:128
	global_store_dword v135, v197, s[58:59]
	global_store_dword v135, v198, s[58:59] offset:128
	global_store_dword v136, v199, s[58:59]
	global_store_dword v136, v200, s[58:59] offset:128
	s_add_u32 s58, s54, 0xd0000
	s_addc_u32 s59, s55, 0
	global_store_dword v133, v201, s[58:59]
	global_store_dword v133, v202, s[58:59] offset:128
	global_store_dword v134, v203, s[58:59]
	global_store_dword v134, v204, s[58:59] offset:128
	global_store_dword v135, v205, s[58:59]
	global_store_dword v135, v206, s[58:59] offset:128
	global_store_dword v136, v207, s[58:59]
	global_store_dword v136, v208, s[58:59] offset:128
	s_waitcnt vmcnt(32)
	v_fmac_f32_e32 v209, v26, v137
	v_fmac_f32_e32 v210, v10, v138
	v_fmac_f32_e32 v211, v27, v137
	v_fmac_f32_e32 v212, v11, v138
	v_fmac_f32_e32 v213, v28, v137
	v_fmac_f32_e32 v214, v12, v138
	v_fmac_f32_e32 v215, v29, v137
	v_fmac_f32_e32 v216, v13, v138
	v_fmac_f32_e32 v217, v30, v137
	v_fmac_f32_e32 v218, v14, v138
	v_fmac_f32_e32 v219, v31, v137
	v_fmac_f32_e32 v220, v15, v138
	v_fmac_f32_e32 v221, v32, v137
	v_fmac_f32_e32 v222, v16, v138
	v_fmac_f32_e32 v223, v33, v137
	v_fmac_f32_e32 v224, v17, v138
	s_add_u32 s58, s54, 0xe0000
	s_addc_u32 s59, s55, 0
	global_store_dword v133, v209, s[58:59]
	global_store_dword v133, v210, s[58:59] offset:128
	global_store_dword v134, v211, s[58:59]
	global_store_dword v134, v212, s[58:59] offset:128
	global_store_dword v135, v213, s[58:59]
	global_store_dword v135, v214, s[58:59] offset:128
	global_store_dword v136, v215, s[58:59]
	global_store_dword v136, v216, s[58:59] offset:128
	s_add_u32 s58, s54, 0xf0000
	s_addc_u32 s59, s55, 0
	global_store_dword v133, v217, s[58:59]
	global_store_dword v133, v218, s[58:59] offset:128
	global_store_dword v134, v219, s[58:59]
	global_store_dword v134, v220, s[58:59] offset:128
	global_store_dword v135, v221, s[58:59]
	global_store_dword v135, v222, s[58:59] offset:128
	global_store_dword v136, v223, s[58:59]
	global_store_dword v136, v224, s[58:59] offset:128
	s_branch .LBB0_1637
